# baseline (speedup 1.0000x reference)
; __device__ __forceinline__ void finishSM(f32x16& p0, f32x16& p1, float alpha, float& l_reg, bf16x8& pa0, bf16x8& pa1, bf16x8& pa2, bf16x8& pa3) {
; #pragma unroll
;   for (int r = 0; r < 16; ++r) p1[r] = __builtin_amdgcn_exp2f(p1[r]);
;   float ps = 0;
; #pragma unroll
;   for (int r = 0; r < 16; ++r) ps += p0[r];
; #pragma unroll
;   for (int r = 0; r < 16; ++r) ps += p1[r];
;   { auto rr = __builtin_amdgcn_permlane32_swap(__float_as_uint(ps), __float_as_uint(ps), false, false);
;     ps = __uint_as_float(rr[0]) + __uint_as_float(rr[1]); }
;   l_reg = l_reg * alpha + ps;
;     ...
;   PK4(p0, 0, pa0); PK4(p0, 8, pa1); PK4(p1, 0, pa2); PK4(p1, 8, pa3);
;     ...
; }
; template <int BUFOFF>
; __device__ __forceinline__ void qkt_mla(f32x16& p0, f32x16& p1, const int* ka, const bf16x8* qr, const char* qlds) {
;   typedef __attribute__((address_space(3))) const bf16x8* lp;
;   p0 = f32x16{}; p1 = f32x16{};
; #pragma unroll
;   for (int d0 = 0; d0 < 12; ++d0) {
;     const int a = ka[d0 & 3] + (d0 >> 2) * 128 + BUFOFF;
;     const bf16x8 b0 = *(lp)(a), b1 = *(lp)(a + 12288);
;     bf16x8 qf;
;     qf = qr[d0];
;     p0 = __builtin_amdgcn_mfma_f32_32x32x16_bf16(b0, qf, p0, 0, 0, 0);
;     p1 = __builtin_amdgcn_mfma_f32_32x32x16_bf16(b1, qf, p1, 0, 0, 0);
;   }
; }
.LBB0_115:
	s_mov_b32 s55, s43
	s_mov_b32 s43, s52
	ds_read_b128 v[64:67], v169 offset:24576
	ds_read_b128 v[68:71], v169 offset:36864
	ds_read_b128 v[214:217], v190 offset:24576
	ds_read_b128 v[218:221], v190 offset:36864
	s_waitcnt lgkmcnt(0)
	v_mfma_f32_32x32x16_bf16 v[80:95], v[64:67], v[140:143], v[226:241]
	v_add_f32_e32 v144, v200, v145
	v_mfma_f32_32x32x16_bf16 v[64:79], v[68:71], v[140:143], v[226:241]
	v_add_f32_e32 v243, v203, v210
	v_add_f32_e32 v244, v202, v208
	v_add_f32_e32 v245, v205, v212
	v_add_f32_e32 v246, v199, v211
	v_add_f32_e32 v247, v201, v213
	v_mfma_f32_32x32x16_bf16 v[80:95], v[214:217], v[136:139], v[80:95]
	v_add_f32_e32 v251, v204, v207
	v_add_f32_e32 v252, v206, v209
	v_mov_b32_e32 v196, v158
	v_add_f32_e32 v144, v172, v144
	v_add_f32_e32 v243, v173, v243
	v_mfma_f32_32x32x16_bf16 v[64:79], v[218:221], v[136:139], v[64:79]
	ds_read_b128 v[214:217], v193 offset:24576
	ds_read_b128 v[218:221], v193 offset:36864
	v_add_f32_e32 v244, v170, v244
	v_add_f32_e32 v245, v171, v245
	v_add_f32_e32 v246, v196, v246
	v_mov_b32_e32 v222, v147
	v_mov_b32_e32 v223, v154
	v_mov_b32_e32 v224, v155
	s_waitcnt lgkmcnt(0)
	v_mfma_f32_32x32x16_bf16 v[80:95], v[214:217], v[132:135], v[80:95]
	v_mfma_f32_32x32x16_bf16 v[64:79], v[218:221], v[132:135], v[64:79]
	ds_read_b128 v[214:217], v192 offset:24576
	ds_read_b128 v[218:221], v192 offset:36864
	s_waitcnt lgkmcnt(0)
	v_mfma_f32_32x32x16_bf16 v[80:95], v[214:217], v[128:131], v[80:95]
	v_mfma_f32_32x32x16_bf16 v[64:79], v[218:221], v[128:131], v[64:79]
	ds_read_b128 v[214:217], v169 offset:24704
	ds_read_b128 v[218:221], v169 offset:36992
	s_waitcnt lgkmcnt(0)
	v_mfma_f32_32x32x16_bf16 v[80:95], v[214:217], v[124:127], v[80:95]
	v_mfma_f32_32x32x16_bf16 v[64:79], v[218:221], v[124:127], v[64:79]
	ds_read_b128 v[214:217], v190 offset:24704
	ds_read_b128 v[218:221], v190 offset:36992
	s_waitcnt lgkmcnt(0)
	v_mfma_f32_32x32x16_bf16 v[80:95], v[214:217], v[120:123], v[80:95]
	v_mfma_f32_32x32x16_bf16 v[64:79], v[218:221], v[120:123], v[64:79]
	ds_read_b128 v[214:217], v193 offset:24704
	ds_read_b128 v[218:221], v193 offset:36992
	s_waitcnt lgkmcnt(0)
	v_mfma_f32_32x32x16_bf16 v[80:95], v[214:217], v[116:119], v[80:95]
	v_mfma_f32_32x32x16_bf16 v[64:79], v[218:221], v[116:119], v[64:79]
	ds_read_b128 v[214:217], v192 offset:24704
	ds_read_b128 v[218:221], v192 offset:36992
	s_waitcnt lgkmcnt(0)
	v_mfma_f32_32x32x16_bf16 v[80:95], v[214:217], v[112:115], v[80:95]
	v_mfma_f32_32x32x16_bf16 v[64:79], v[218:221], v[112:115], v[64:79]
	ds_read_b128 v[214:217], v169 offset:24832
	ds_read_b128 v[218:221], v169 offset:37120
	s_waitcnt lgkmcnt(0)
	v_mfma_f32_32x32x16_bf16 v[80:95], v[214:217], v[108:111], v[80:95]
	v_mfma_f32_32x32x16_bf16 v[64:79], v[218:221], v[108:111], v[64:79]
	ds_read_b128 v[214:217], v190 offset:24832
	ds_read_b128 v[218:221], v190 offset:37120
	s_waitcnt lgkmcnt(0)
	v_mfma_f32_32x32x16_bf16 v[80:95], v[214:217], v[104:107], v[80:95]
	v_mfma_f32_32x32x16_bf16 v[64:79], v[218:221], v[104:107], v[64:79]
	ds_read_b128 v[214:217], v193 offset:24832
	ds_read_b128 v[218:221], v193 offset:37120
	s_waitcnt lgkmcnt(0)
	v_mfma_f32_32x32x16_bf16 v[80:95], v[214:217], v[100:103], v[80:95]
	v_mfma_f32_32x32x16_bf16 v[64:79], v[218:221], v[100:103], v[64:79]
	ds_read_b128 v[214:217], v192 offset:24832
	ds_read_b128 v[218:221], v192 offset:37120
	s_waitcnt lgkmcnt(0)
	v_mfma_f32_32x32x16_bf16 v[80:95], v[214:217], v[96:99], v[80:95]
	v_mov_b32_e32 v214, v159
	v_mov_b32_e32 v215, v152
	v_mov_b32_e32 v216, v153
	v_mov_b32_e32 v217, v150
	v_add_f32_e32 v247, v214, v247
	v_add_f32_e32 v251, v215, v251
	v_add_f32_e32 v252, v216, v252
	v_mfma_f32_32x32x16_bf16 v[64:79], v[218:221], v[96:99], v[64:79]
	v_mov_b32_e32 v218, v151
	v_mov_b32_e32 v219, v148
	v_mov_b32_e32 v220, v149
	v_mov_b32_e32 v221, v146
	v_add_f32_e32 v144, v217, v144
	v_add_f32_e32 v243, v218, v243
	v_add_f32_e32 v244, v219, v244
	v_add_f32_e32 v245, v220, v245
	v_add_f32_e32 v246, v221, v246
	v_add_f32_e32 v247, v222, v247
	v_add_f32_e32 v251, v223, v251
	v_add_f32_e32 v252, v224, v252
	v_add_f32_e32 v144, v144, v243
	v_add_f32_e32 v244, v244, v245
	v_add_f32_e32 v246, v246, v247
	v_add_f32_e32 v251, v251, v252
	v_add_f32_e32 v144, v144, v244
	v_add_f32_e32 v246, v246, v251
	v_add_f32_e32 v158, v144, v246
	v_mov_b32_e32 v159, v158
	v_cvt_pk_bf16_f32 v144, v145, v210
	v_cvt_pk_bf16_f32 v145, v208, v212
	v_cvt_pk_bf16_f32 v146, v211, v213
	v_cvt_pk_bf16_f32 v147, v207, v209
	v_cvt_pk_bf16_f32 v148, v200, v203
	v_cvt_pk_bf16_f32 v149, v202, v205
	v_cvt_pk_bf16_f32 v150, v199, v201
	v_cvt_pk_bf16_f32 v151, v204, v206
	v_cvt_pk_bf16_f32 v152, v172, v173
	v_cvt_pk_bf16_f32 v153, v170, v171
	v_cvt_pk_bf16_f32 v154, v196, v214
	s_nop 1
	v_permlane32_swap_b32_e32 v158, v159
	v_cvt_pk_bf16_f32 v155, v215, v216
	v_cvt_pk_bf16_f32 v170, v217, v218
	v_cvt_pk_bf16_f32 v171, v219, v220
	v_cvt_pk_bf16_f32 v172, v221, v222
	v_cvt_pk_bf16_f32 v173, v223, v224
	v_readlane_b32 s58, v249, 37
	v_readlane_b32 s59, v249, 38
	s_add_u32 s56, s58, s47
	s_addc_u32 s57, s59, s50
	s_add_u32 s4, s56, 0x17060000
	s_addc_u32 s5, s57, 0
	s_add_u32 s58, s58, s14
	s_addc_u32 s59, s59, s15
	s_add_u32 s60, s58, 0x1a040000
	s_mov_b32 m0, s41
	s_addc_u32 s61, s59, 0
	s_lshl_b32 s52, s54, 14
	s_add_i32 s62, s40, s52
	global_load_lds_dwordx4 v188, s[4:5]
	s_mov_b32 m0, s42
	s_nop 0
	global_load_lds_dwordx4 v189, s[4:5]
	s_add_i32 m0, s41, 0x4000
	s_nop 0
	global_load_lds_dwordx4 v191, s[4:5]
	s_mov_b32 m0, s62
	s_nop 0
	global_load_lds_dwordx4 v194, s[60:61]
	s_add_i32 m0, s62, 0x2000
	s_nop 0
	global_load_lds_dwordx4 v195, s[60:61]
	s_lshl_b32 s60, s43, 14
	v_add_u32_e32 v196, s60, v167
	ds_read_b64_tr_b16 v[200:201], v196 offset:0
	ds_read_b64_tr_b16 v[202:203], v196 offset:0x800
	ds_read_b64_tr_b16 v[204:205], v196 offset:0x1000
	ds_read_b64_tr_b16 v[206:207], v196 offset:0x1800
	ds_read_b64_tr_b16 v[208:209], v196 offset:0x2000
	ds_read_b64_tr_b16 v[210:211], v196 offset:0x2800
	ds_read_b64_tr_b16 v[212:213], v196 offset:0x3000
	ds_read_b64_tr_b16 v[214:215], v196 offset:0x3800
	s_nop 0
	s_waitcnt lgkmcnt(6)
; #define SBAR() __builtin_amdgcn_sched_barrier(0)
; template <int MLA>
; __device__ __forceinline__ void partialSM(f32x16& p0, f32x16& p1, float& m_reg, float& mn, float& alpha) {
;   constexpr float SCALE = AttC<MLA>::SCALE;
;   constexpr float C = SCALE * 1.4426950408889634f;
;   float pmax = p0[0];
; #pragma unroll
;   for (int r = 1; r < 16; ++r) pmax = fmaxf(pmax, p0[r]);
; #pragma unroll
;   for (int r = 0; r < 16; ++r) pmax = fmaxf(pmax, p1[r]);
;   { auto rr = __builtin_amdgcn_permlane32_swap(__float_as_uint(pmax), __float_as_uint(pmax), false, false);
;     pmax = fmaxf(__uint_as_float(rr[0]), __uint_as_float(rr[1])); }
;   if (__builtin_expect(__all(pmax - m_reg <= THR / SCALE), 1)) { mn = m_reg; alpha = 1.f; }
;   else { mn = fmaxf(m_reg, pmax); alpha = __builtin_amdgcn_exp2f((m_reg - mn) * C); m_reg = mn; }
;   float mnC = -mn * C;
; #pragma unroll
;   for (int r = 0; r < 16; ++r) p0[r] = fmaf(p0[r], C, mnC);
; #pragma unroll
;   for (int r = 0; r < 16; ++r) p1[r] = fmaf(p1[r], C, mnC);
; #pragma unroll
;   for (int r = 0; r < 16; ++r) p0[r] = __builtin_amdgcn_exp2f(p0[r]);
; }
; __device__ __forceinline__ void finishSM(f32x16& p0, f32x16& p1, float alpha, float& l_reg, bf16x8& pa0, bf16x8& pa1, bf16x8& pa2, bf16x8& pa3) {
; #pragma unroll
;   for (int r = 0; r < 16; ++r) p1[r] = __builtin_amdgcn_exp2f(p1[r]);
;   float ps = 0;
; #pragma unroll
;   for (int r = 0; r < 16; ++r) ps += p0[r];
; #pragma unroll
;   for (int r = 0; r < 16; ++r) ps += p1[r];
;   { auto rr = __builtin_amdgcn_permlane32_swap(__float_as_uint(ps), __float_as_uint(ps), false, false);
;     ps = __uint_as_float(rr[0]) + __uint_as_float(rr[1]); }
;   l_reg = l_reg * alpha + ps;
;     ...
;   PK4(p0, 0, pa0); PK4(p0, 8, pa1); PK4(p1, 0, pa2); PK4(p1, 8, pa3);
;     ...
; }
; template <int D0> __device__ __forceinline__ void pv_one_t(f32x16& od, int vb, bf16x8 pa0, bf16x8 pa1, bf16x8 pa2, bf16x8 pa3) {
;   const s16x4 l0 = tr_read<v_rd_off(D0, 0, 0)>(vb), h0 = tr_read<v_rd_off(D0, 0, 1)>(vb), l1 = tr_read<v_rd_off(D0, 1, 0)>(vb), h1 = tr_read<v_rd_off(D0, 1, 1)>(vb);
;   const s16x4 l2 = tr_read<v_rd_off(D0, 2, 0)>(vb), h2 = tr_read<v_rd_off(D0, 2, 1)>(vb), l3 = tr_read<v_rd_off(D0, 3, 0)>(vb), h3 = tr_read<v_rd_off(D0, 3, 1)>(vb);
;   asm volatile("s_waitcnt lgkmcnt(0)" ::: "memory"); SBAR();
;     ...
;   od = __builtin_amdgcn_mfma_f32_32x32x16_bf16(PK(l0, h0), pa0, od, 0, 0, 0);
	v_mfma_f32_32x32x16_bf16 v[0:15], v[200:203], v[144:147], v[0:15]
	ds_read_b64_tr_b16 v[200:201], v196 offset:0x200
	ds_read_b64_tr_b16 v[202:203], v196 offset:0xa00
	s_waitcnt lgkmcnt(6)
	v_mfma_f32_32x32x16_bf16 v[0:15], v[204:207], v[148:151], v[0:15]
	ds_read_b64_tr_b16 v[204:205], v196 offset:0x1200
	ds_read_b64_tr_b16 v[206:207], v196 offset:0x1a00
	s_waitcnt lgkmcnt(6)
	v_mfma_f32_32x32x16_bf16 v[0:15], v[208:211], v[152:155], v[0:15]
	ds_read_b64_tr_b16 v[208:209], v196 offset:0x2200
	ds_read_b64_tr_b16 v[210:211], v196 offset:0x2a00
	s_waitcnt lgkmcnt(6)
	v_mfma_f32_32x32x16_bf16 v[0:15], v[212:215], v[170:173], v[0:15]
	ds_read_b64_tr_b16 v[212:213], v196 offset:0x3200
	ds_read_b64_tr_b16 v[214:215], v196 offset:0x3a00
	s_waitcnt lgkmcnt(6)
	v_mfma_f32_32x32x16_bf16 v[48:63], v[200:203], v[144:147], v[48:63]
	ds_read_b64_tr_b16 v[200:201], v196 offset:0x400
	ds_read_b64_tr_b16 v[202:203], v196 offset:0xc00
	s_waitcnt lgkmcnt(6)
	v_mfma_f32_32x32x16_bf16 v[48:63], v[204:207], v[148:151], v[48:63]
	ds_read_b64_tr_b16 v[204:205], v196 offset:0x1400
	ds_read_b64_tr_b16 v[206:207], v196 offset:0x1c00
	s_waitcnt lgkmcnt(6)
	v_mfma_f32_32x32x16_bf16 v[48:63], v[208:211], v[152:155], v[48:63]
	ds_read_b64_tr_b16 v[208:209], v196 offset:0x2400
	ds_read_b64_tr_b16 v[210:211], v196 offset:0x2c00
	s_waitcnt lgkmcnt(6)
	v_mfma_f32_32x32x16_bf16 v[48:63], v[212:215], v[170:173], v[48:63]
	ds_read_b64_tr_b16 v[212:213], v196 offset:0x3400
	ds_read_b64_tr_b16 v[214:215], v196 offset:0x3c00
	s_waitcnt lgkmcnt(6)
	v_mfma_f32_32x32x16_bf16 v[32:47], v[200:203], v[144:147], v[32:47]
	ds_read_b64_tr_b16 v[200:201], v196 offset:0x600
	ds_read_b64_tr_b16 v[202:203], v196 offset:0xe00
	s_waitcnt lgkmcnt(6)
	v_mfma_f32_32x32x16_bf16 v[32:47], v[204:207], v[148:151], v[32:47]
	ds_read_b64_tr_b16 v[204:205], v196 offset:0x1600
	ds_read_b64_tr_b16 v[206:207], v196 offset:0x1e00
	s_waitcnt lgkmcnt(6)
	v_mfma_f32_32x32x16_bf16 v[32:47], v[208:211], v[152:155], v[32:47]
	ds_read_b64_tr_b16 v[208:209], v196 offset:0x2600
	ds_read_b64_tr_b16 v[210:211], v196 offset:0x2e00
	s_waitcnt lgkmcnt(6)
	v_mfma_f32_32x32x16_bf16 v[32:47], v[212:215], v[170:173], v[32:47]
	ds_read_b64_tr_b16 v[212:213], v196 offset:0x3600
	ds_read_b64_tr_b16 v[214:215], v196 offset:0x3e00
	s_waitcnt lgkmcnt(6)
	v_mfma_f32_32x32x16_bf16 v[16:31], v[200:203], v[144:147], v[16:31]
	v_max_f32_e32 v144, v80, v81
	v_max3_f32 v144, v144, v82, v83
	v_max3_f32 v144, v144, v84, v85
	v_max3_f32 v144, v144, v86, v87
	v_max3_f32 v144, v144, v88, v89
	v_max3_f32 v144, v144, v90, v91
	v_max3_f32 v144, v144, v92, v93
	s_waitcnt lgkmcnt(4)
	v_mfma_f32_32x32x16_bf16 v[16:31], v[204:207], v[148:151], v[16:31]
	v_max3_f32 v144, v144, v94, v95
	v_max3_f32 v144, v144, v64, v65
	v_max3_f32 v144, v144, v66, v67
	v_max3_f32 v144, v144, v68, v69
	v_max3_f32 v144, v144, v70, v71
	v_max3_f32 v144, v144, v72, v73
	v_max3_f32 v144, v144, v74, v75
	v_max3_f32 v144, v144, v76, v77
	s_waitcnt lgkmcnt(2)
	v_mfma_f32_32x32x16_bf16 v[16:31], v[208:211], v[152:155], v[16:31]
	v_max3_f32 v144, v144, v78, v79
	v_mov_b32_e32 v145, v144
	s_nop 1
	v_permlane32_swap_b32_e32 v144, v145
	v_max_f32_e32 v144, v144, v145
	v_cmp_ge_f32_e32 vcc, s63, v144
	s_waitcnt lgkmcnt(0)
	v_mfma_f32_32x32x16_bf16 v[16:31], v[212:215], v[170:173], v[16:31]
	s_waitcnt vmcnt(0) lgkmcnt(0)
	s_barrier
	s_cmp_eq_u64 vcc, exec
	s_cbranch_scc0 .Lrare_m1
	v_mov_b32_e32 v152, 1.0
.LBB0_117:
	v_exp_f32_e32 v155, v64
	v_exp_f32_e32 v170, v65
	v_exp_f32_e32 v171, v66
	v_exp_f32_e32 v172, v67
	v_exp_f32_e32 v173, v68
	v_exp_f32_e32 v197, v69
	v_exp_f32_e32 v199, v70
	v_exp_f32_e32 v200, v71
	v_exp_f32_e32 v201, v72
	v_exp_f32_e32 v202, v73
	v_exp_f32_e32 v203, v74
	v_exp_f32_e32 v204, v75
	v_exp_f32_e32 v205, v76
	v_exp_f32_e32 v222, v77
	v_exp_f32_e32 v223, v78
	v_exp_f32_e32 v154, v79
	v_exp_f32_e32 v206, v80
	v_exp_f32_e32 v207, v81
	v_exp_f32_e32 v208, v82
	v_exp_f32_e32 v209, v83
	v_exp_f32_e32 v210, v84
	v_exp_f32_e32 v211, v85
	v_exp_f32_e32 v212, v86
	v_exp_f32_e32 v213, v87
	v_exp_f32_e32 v214, v88
	v_exp_f32_e32 v215, v89
	v_exp_f32_e32 v216, v90
	v_exp_f32_e32 v217, v91
	v_exp_f32_e32 v218, v92
	v_exp_f32_e32 v219, v93
	v_exp_f32_e32 v220, v94
	v_exp_f32_e32 v221, v95
	ds_read_b128 v[64:67], v169
	ds_read_b128 v[68:71], v169 offset:12288
	ds_read_b128 v[144:147], v190
	ds_read_b128 v[148:151], v190 offset:12288
	v_mov_b32_e32 v224, v155
	s_waitcnt lgkmcnt(0)
	v_mfma_f32_32x32x16_bf16 v[80:95], v[64:67], v[140:143], v[226:241]
	v_mfma_f32_32x32x16_bf16 v[64:79], v[68:71], v[140:143], v[226:241]
	v_mov_b32_e32 v225, v154
	v_mfma_f32_32x32x16_bf16 v[80:95], v[144:147], v[136:139], v[80:95]
	v_mfma_f32_32x32x16_bf16 v[64:79], v[148:151], v[136:139], v[64:79]
	ds_read_b128 v[144:147], v193
	ds_read_b128 v[148:151], v193 offset:12288
	s_waitcnt lgkmcnt(0)
	v_mfma_f32_32x32x16_bf16 v[80:95], v[144:147], v[132:135], v[80:95]
	v_mfma_f32_32x32x16_bf16 v[64:79], v[148:151], v[132:135], v[64:79]
	ds_read_b128 v[144:147], v192
	ds_read_b128 v[148:151], v192 offset:12288
	s_waitcnt lgkmcnt(0)
	v_mfma_f32_32x32x16_bf16 v[80:95], v[144:147], v[128:131], v[80:95]
	v_mfma_f32_32x32x16_bf16 v[64:79], v[148:151], v[128:131], v[64:79]
	ds_read_b128 v[144:147], v169 offset:128
	ds_read_b128 v[148:151], v169 offset:12416
	s_waitcnt lgkmcnt(0)
	v_mfma_f32_32x32x16_bf16 v[80:95], v[144:147], v[124:127], v[80:95]
	v_mfma_f32_32x32x16_bf16 v[64:79], v[148:151], v[124:127], v[64:79]
	ds_read_b128 v[144:147], v190 offset:128
	ds_read_b128 v[148:151], v190 offset:12416
	s_waitcnt lgkmcnt(0)
; __device__ __forceinline__ void finishSM(f32x16& p0, f32x16& p1, float alpha, float& l_reg, bf16x8& pa0, bf16x8& pa1, bf16x8& pa2, bf16x8& pa3) {
; #pragma unroll
;   for (int r = 0; r < 16; ++r) p1[r] = __builtin_amdgcn_exp2f(p1[r]);
;   float ps = 0;
; #pragma unroll
;   for (int r = 0; r < 16; ++r) ps += p0[r];
; #pragma unroll
;   for (int r = 0; r < 16; ++r) ps += p1[r];
;   { auto rr = __builtin_amdgcn_permlane32_swap(__float_as_uint(ps), __float_as_uint(ps), false, false);
;     ps = __uint_as_float(rr[0]) + __uint_as_float(rr[1]); }
;   l_reg = l_reg * alpha + ps;
;     ...
;   PK4(p0, 0, pa0); PK4(p0, 8, pa1); PK4(p1, 0, pa2); PK4(p1, 8, pa3);
;     ...
; }
	v_mfma_f32_32x32x16_bf16 v[80:95], v[144:147], v[120:123], v[80:95]
	v_mfma_f32_32x32x16_bf16 v[64:79], v[148:151], v[120:123], v[64:79]
	ds_read_b128 v[144:147], v193 offset:128
	ds_read_b128 v[148:151], v193 offset:12416
	s_waitcnt lgkmcnt(0)
	v_mfma_f32_32x32x16_bf16 v[80:95], v[144:147], v[116:119], v[80:95]
	v_mfma_f32_32x32x16_bf16 v[64:79], v[148:151], v[116:119], v[64:79]
	ds_read_b128 v[144:147], v192 offset:128
	ds_read_b128 v[148:151], v192 offset:12416
	s_waitcnt lgkmcnt(0)
	v_mfma_f32_32x32x16_bf16 v[80:95], v[144:147], v[112:115], v[80:95]
	v_mfma_f32_32x32x16_bf16 v[64:79], v[148:151], v[112:115], v[64:79]
	ds_read_b128 v[144:147], v169 offset:256
	ds_read_b128 v[148:151], v169 offset:12544
	s_waitcnt lgkmcnt(0)
	v_mfma_f32_32x32x16_bf16 v[80:95], v[144:147], v[108:111], v[80:95]
	v_mfma_f32_32x32x16_bf16 v[64:79], v[148:151], v[108:111], v[64:79]
	ds_read_b128 v[144:147], v190 offset:256
	ds_read_b128 v[148:151], v190 offset:12544
	s_waitcnt lgkmcnt(0)
	v_mfma_f32_32x32x16_bf16 v[80:95], v[144:147], v[104:107], v[80:95]
	v_mfma_f32_32x32x16_bf16 v[64:79], v[148:151], v[104:107], v[64:79]
	ds_read_b128 v[144:147], v193 offset:256
	ds_read_b128 v[148:151], v193 offset:12544
	s_waitcnt lgkmcnt(0)
	v_mfma_f32_32x32x16_bf16 v[80:95], v[144:147], v[100:103], v[80:95]
	v_mfma_f32_32x32x16_bf16 v[64:79], v[148:151], v[100:103], v[64:79]
	ds_read_b128 v[144:147], v192 offset:256
	ds_read_b128 v[148:151], v192 offset:12544
	s_waitcnt lgkmcnt(0)
	v_mfma_f32_32x32x16_bf16 v[80:95], v[144:147], v[96:99], v[80:95]
	v_add_f32_e32 v144, v214, v206
	v_add_f32_e32 v243, v215, v207
	v_add_f32_e32 v244, v216, v208
	v_add_f32_e32 v245, v217, v209
	v_add_f32_e32 v246, v218, v210
	v_add_f32_e32 v247, v219, v211
	v_add_f32_e32 v251, v220, v212
	v_add_f32_e32 v252, v221, v213
	v_add_f32_e32 v144, v224, v144
	v_add_f32_e32 v243, v170, v243
	v_add_f32_e32 v244, v171, v244
	v_add_f32_e32 v245, v172, v245
	v_add_f32_e32 v246, v173, v246
	v_add_f32_e32 v247, v197, v247
	v_add_f32_e32 v251, v199, v251
	v_add_f32_e32 v252, v200, v252
	v_add_f32_e32 v144, v201, v144
	v_add_f32_e32 v243, v202, v243
	v_mfma_f32_32x32x16_bf16 v[64:79], v[148:151], v[96:99], v[64:79]
	v_add_f32_e32 v244, v203, v244
	v_add_f32_e32 v245, v204, v245
	v_add_f32_e32 v246, v205, v246
	v_add_f32_e32 v247, v222, v247
	v_add_f32_e32 v251, v223, v251
	v_add_f32_e32 v252, v225, v252
	v_add_f32_e32 v144, v144, v243
	v_add_f32_e32 v244, v244, v245
	v_add_f32_e32 v246, v246, v247
	v_add_f32_e32 v251, v251, v252
	v_add_f32_e32 v144, v144, v244
	v_add_f32_e32 v246, v246, v251
	v_add_f32_e32 v154, v144, v246
	v_mov_b32_e32 v155, v154
	v_cvt_pk_bf16_f32 v144, v206, v207
	v_cvt_pk_bf16_f32 v145, v208, v209
	v_cvt_pk_bf16_f32 v146, v210, v211
	v_cvt_pk_bf16_f32 v147, v212, v213
	s_nop 1
	v_permlane32_swap_b32_e32 v154, v155
	v_cvt_pk_bf16_f32 v148, v214, v215
	v_cvt_pk_bf16_f32 v149, v216, v217
	v_cvt_pk_bf16_f32 v150, v218, v219
	v_cvt_pk_bf16_f32 v151, v220, v221
	v_cvt_pk_bf16_f32 v170, v224, v170
	v_cvt_pk_bf16_f32 v171, v171, v172
	v_cvt_pk_bf16_f32 v172, v173, v197
	v_cvt_pk_bf16_f32 v173, v199, v200
	v_cvt_pk_bf16_f32 v200, v201, v202
	v_cvt_pk_bf16_f32 v201, v203, v204
	v_cvt_pk_bf16_f32 v202, v205, v222
	v_cvt_pk_bf16_f32 v203, v223, v225
	s_nop 0
	s_add_u32 s4, s56, 0x17090000
	s_addc_u32 s5, s57, 0
	s_add_u32 s56, s58, 0x1a060000
	s_mov_b32 m0, s16
	s_addc_u32 s57, s59, 0
	s_add_i32 s58, s40, s60
	global_load_lds_dwordx4 v188, s[4:5]
	s_mov_b32 m0, s17
	s_nop 0
	global_load_lds_dwordx4 v189, s[4:5]
	s_mov_b32 m0, s44
	s_nop 0
	global_load_lds_dwordx4 v191, s[4:5]
	s_mov_b32 m0, s58
	s_nop 0
	global_load_lds_dwordx4 v194, s[56:57]
	s_add_i32 m0, s58, 0x2000
	s_nop 0
	global_load_lds_dwordx4 v195, s[56:57]
	v_lshl_add_u32 v197, s55, 14, v167
	ds_read_b64_tr_b16 v[204:205], v197 offset:0
	ds_read_b64_tr_b16 v[206:207], v197 offset:0x800
	ds_read_b64_tr_b16 v[208:209], v197 offset:0x1000
	ds_read_b64_tr_b16 v[210:211], v197 offset:0x1800
	ds_read_b64_tr_b16 v[212:213], v197 offset:0x2000
	ds_read_b64_tr_b16 v[214:215], v197 offset:0x2800
	ds_read_b64_tr_b16 v[216:217], v197 offset:0x3000
	ds_read_b64_tr_b16 v[218:219], v197 offset:0x3800
	s_nop 0
	s_waitcnt lgkmcnt(6)
; #define SBAR() __builtin_amdgcn_sched_barrier(0)
; template <int MLA>
; __device__ __forceinline__ void partialSM(f32x16& p0, f32x16& p1, float& m_reg, float& mn, float& alpha) {
;     ...
;   float pmax = p0[0];
; #pragma unroll
;   for (int r = 1; r < 16; ++r) pmax = fmaxf(pmax, p0[r]);
; #pragma unroll
;   for (int r = 0; r < 16; ++r) pmax = fmaxf(pmax, p1[r]);
;   { auto rr = __builtin_amdgcn_permlane32_swap(__float_as_uint(pmax), __float_as_uint(pmax), false, false);
;     pmax = fmaxf(__uint_as_float(rr[0]), __uint_as_float(rr[1])); }
;   if (__builtin_expect(__all(pmax - m_reg <= THR / SCALE), 1)) { mn = m_reg; alpha = 1.f; }
;   else { mn = fmaxf(m_reg, pmax); alpha = __builtin_amdgcn_exp2f((m_reg - mn) * C); m_reg = mn; }
; template <int D0> __device__ __forceinline__ void pv_one_t(f32x16& od, int vb, bf16x8 pa0, bf16x8 pa1, bf16x8 pa2, bf16x8 pa3) {
;   const s16x4 l0 = tr_read<v_rd_off(D0, 0, 0)>(vb), h0 = tr_read<v_rd_off(D0, 0, 1)>(vb), l1 = tr_read<v_rd_off(D0, 1, 0)>(vb), h1 = tr_read<v_rd_off(D0, 1, 1)>(vb);
;   const s16x4 l2 = tr_read<v_rd_off(D0, 2, 0)>(vb), h2 = tr_read<v_rd_off(D0, 2, 1)>(vb), l3 = tr_read<v_rd_off(D0, 3, 0)>(vb), h3 = tr_read<v_rd_off(D0, 3, 1)>(vb);
;   asm volatile("s_waitcnt lgkmcnt(0)" ::: "memory"); SBAR();
;     ...
;   od = __builtin_amdgcn_mfma_f32_32x32x16_bf16(PK(l0, h0), pa0, od, 0, 0, 0);
;   od = __builtin_amdgcn_mfma_f32_32x32x16_bf16(PK(l1, h1), pa1, od, 0, 0, 0);
;   od = __builtin_amdgcn_mfma_f32_32x32x16_bf16(PK(l2, h2), pa2, od, 0, 0, 0);
;   od = __builtin_amdgcn_mfma_f32_32x32x16_bf16(PK(l3, h3), pa3, od, 0, 0, 0);
;     ...
; }
	v_mfma_f32_32x32x16_bf16 v[0:15], v[204:207], v[144:147], v[0:15]
	ds_read_b64_tr_b16 v[204:205], v197 offset:0x200
	ds_read_b64_tr_b16 v[206:207], v197 offset:0xa00
	s_waitcnt lgkmcnt(6)
	v_mfma_f32_32x32x16_bf16 v[0:15], v[208:211], v[148:151], v[0:15]
	ds_read_b64_tr_b16 v[208:209], v197 offset:0x1200
	ds_read_b64_tr_b16 v[210:211], v197 offset:0x1a00
	s_waitcnt lgkmcnt(6)
	v_mfma_f32_32x32x16_bf16 v[0:15], v[212:215], v[170:173], v[0:15]
	ds_read_b64_tr_b16 v[212:213], v197 offset:0x2200
	ds_read_b64_tr_b16 v[214:215], v197 offset:0x2a00
	s_waitcnt lgkmcnt(6)
	v_mfma_f32_32x32x16_bf16 v[0:15], v[216:219], v[200:203], v[0:15]
	ds_read_b64_tr_b16 v[216:217], v197 offset:0x3200
	ds_read_b64_tr_b16 v[218:219], v197 offset:0x3a00
	s_waitcnt lgkmcnt(6)
	v_mfma_f32_32x32x16_bf16 v[48:63], v[204:207], v[144:147], v[48:63]
	ds_read_b64_tr_b16 v[204:205], v197 offset:0x400
	ds_read_b64_tr_b16 v[206:207], v197 offset:0xc00
	s_waitcnt lgkmcnt(6)
	v_mfma_f32_32x32x16_bf16 v[48:63], v[208:211], v[148:151], v[48:63]
	ds_read_b64_tr_b16 v[208:209], v197 offset:0x1400
	ds_read_b64_tr_b16 v[210:211], v197 offset:0x1c00
	s_waitcnt lgkmcnt(6)
	v_mfma_f32_32x32x16_bf16 v[48:63], v[212:215], v[170:173], v[48:63]
	ds_read_b64_tr_b16 v[212:213], v197 offset:0x2400
	ds_read_b64_tr_b16 v[214:215], v197 offset:0x2c00
	s_waitcnt lgkmcnt(6)
	v_mfma_f32_32x32x16_bf16 v[48:63], v[216:219], v[200:203], v[48:63]
	ds_read_b64_tr_b16 v[216:217], v197 offset:0x3400
	ds_read_b64_tr_b16 v[218:219], v197 offset:0x3c00
	s_waitcnt lgkmcnt(6)
	v_mfma_f32_32x32x16_bf16 v[32:47], v[204:207], v[144:147], v[32:47]
	ds_read_b64_tr_b16 v[204:205], v197 offset:0x600
	ds_read_b64_tr_b16 v[206:207], v197 offset:0xe00
	s_waitcnt lgkmcnt(6)
	v_mfma_f32_32x32x16_bf16 v[32:47], v[208:211], v[148:151], v[32:47]
	ds_read_b64_tr_b16 v[208:209], v197 offset:0x1600
	ds_read_b64_tr_b16 v[210:211], v197 offset:0x1e00
	s_waitcnt lgkmcnt(6)
	v_mfma_f32_32x32x16_bf16 v[32:47], v[212:215], v[170:173], v[32:47]
	ds_read_b64_tr_b16 v[212:213], v197 offset:0x2600
	ds_read_b64_tr_b16 v[214:215], v197 offset:0x2e00
	s_waitcnt lgkmcnt(6)
	v_mfma_f32_32x32x16_bf16 v[32:47], v[216:219], v[200:203], v[32:47]
	ds_read_b64_tr_b16 v[216:217], v197 offset:0x3600
	ds_read_b64_tr_b16 v[218:219], v197 offset:0x3e00
	s_waitcnt lgkmcnt(6)
	v_mfma_f32_32x32x16_bf16 v[16:31], v[204:207], v[144:147], v[16:31]
	v_max_f32_e32 v144, v80, v81
	v_max3_f32 v144, v144, v82, v83
	v_max3_f32 v144, v144, v84, v85
	v_max3_f32 v144, v144, v86, v87
	v_max3_f32 v144, v144, v88, v89
	v_max3_f32 v144, v144, v90, v91
	v_max3_f32 v144, v144, v92, v93
	s_waitcnt lgkmcnt(4)
	v_mfma_f32_32x32x16_bf16 v[16:31], v[208:211], v[148:151], v[16:31]
	v_max3_f32 v144, v144, v94, v95
	v_max3_f32 v144, v144, v64, v65
	v_max3_f32 v144, v144, v66, v67
	v_max3_f32 v144, v144, v68, v69
	v_max3_f32 v144, v144, v70, v71
	v_max3_f32 v144, v144, v72, v73
	v_max3_f32 v144, v144, v74, v75
	v_max3_f32 v144, v144, v76, v77
	s_waitcnt lgkmcnt(2)
	v_mfma_f32_32x32x16_bf16 v[16:31], v[212:215], v[170:173], v[16:31]
	v_max3_f32 v144, v144, v78, v79
	v_mov_b32_e32 v145, v144
	s_nop 1
	v_permlane32_swap_b32_e32 v144, v145
	v_max_f32_e32 v144, v144, v145
	v_cmp_ge_f32_e32 vcc, s63, v144
	s_waitcnt lgkmcnt(0)
	v_mfma_f32_32x32x16_bf16 v[16:31], v[216:219], v[200:203], v[16:31]
	s_waitcnt vmcnt(0) lgkmcnt(0)
	s_barrier
	s_cmp_eq_u64 vcc, exec
	s_cbranch_scc0 .Lrare_m2
	v_mov_b32_e32 v144, 1.0

; template <int MLA>
; __device__ __forceinline__ void partialSM(f32x16& p0, f32x16& p1, float& m_reg, float& mn, float& alpha) {
;     ...
;   if (__builtin_expect(__all(pmax - m_reg <= THR / SCALE), 1)) { mn = m_reg; alpha = 1.f; }
;   else { mn = fmaxf(m_reg, pmax); alpha = __builtin_amdgcn_exp2f((m_reg - mn) * C); m_reg = mn; }
;   float mnC = -mn * C;
; #pragma unroll
;   for (int r = 0; r < 16; ++r) p0[r] = fmaf(p0[r], C, mnC);
; #pragma unroll
;   for (int r = 0; r < 16; ++r) p1[r] = fmaf(p1[r], C, mnC);
.Lrare_m2:
	v_max_f32_e32 v242, 0, v144
	v_exp_f32_e64 v144, -v242
	s_nop 0
	v_pk_mul_f32 v[14:15], v[14:15], v[144:145] op_sel_hi:[1,0]
	v_pk_mul_f32 v[12:13], v[12:13], v[144:145] op_sel_hi:[1,0]
	v_pk_mul_f32 v[10:11], v[10:11], v[144:145] op_sel_hi:[1,0]
	v_pk_mul_f32 v[8:9], v[8:9], v[144:145] op_sel_hi:[1,0]
	v_pk_mul_f32 v[6:7], v[6:7], v[144:145] op_sel_hi:[1,0]
	v_pk_mul_f32 v[4:5], v[4:5], v[144:145] op_sel_hi:[1,0]
	v_pk_mul_f32 v[2:3], v[2:3], v[144:145] op_sel_hi:[1,0]
	v_pk_mul_f32 v[0:1], v[0:1], v[144:145] op_sel_hi:[1,0]
	v_pk_mul_f32 v[62:63], v[62:63], v[144:145] op_sel_hi:[1,0]
	v_pk_mul_f32 v[60:61], v[60:61], v[144:145] op_sel_hi:[1,0]
	v_pk_mul_f32 v[58:59], v[58:59], v[144:145] op_sel_hi:[1,0]
	v_pk_mul_f32 v[56:57], v[56:57], v[144:145] op_sel_hi:[1,0]
	v_pk_mul_f32 v[54:55], v[54:55], v[144:145] op_sel_hi:[1,0]
	v_pk_mul_f32 v[52:53], v[52:53], v[144:145] op_sel_hi:[1,0]
	v_pk_mul_f32 v[50:51], v[50:51], v[144:145] op_sel_hi:[1,0]
	v_pk_mul_f32 v[48:49], v[48:49], v[144:145] op_sel_hi:[1,0]
	v_pk_mul_f32 v[46:47], v[46:47], v[144:145] op_sel_hi:[1,0]
	v_pk_mul_f32 v[44:45], v[44:45], v[144:145] op_sel_hi:[1,0]
	v_pk_mul_f32 v[42:43], v[42:43], v[144:145] op_sel_hi:[1,0]
	v_pk_mul_f32 v[40:41], v[40:41], v[144:145] op_sel_hi:[1,0]
	v_pk_mul_f32 v[38:39], v[38:39], v[144:145] op_sel_hi:[1,0]
	v_pk_mul_f32 v[36:37], v[36:37], v[144:145] op_sel_hi:[1,0]
	v_pk_mul_f32 v[34:35], v[34:35], v[144:145] op_sel_hi:[1,0]
	v_pk_mul_f32 v[32:33], v[32:33], v[144:145] op_sel_hi:[1,0]
	v_pk_mul_f32 v[30:31], v[30:31], v[144:145] op_sel_hi:[1,0]
	v_pk_mul_f32 v[28:29], v[28:29], v[144:145] op_sel_hi:[1,0]
	v_pk_mul_f32 v[26:27], v[26:27], v[144:145] op_sel_hi:[1,0]
	v_pk_mul_f32 v[24:25], v[24:25], v[144:145] op_sel_hi:[1,0]
	v_pk_mul_f32 v[22:23], v[22:23], v[144:145] op_sel_hi:[1,0]
	v_pk_mul_f32 v[20:21], v[20:21], v[144:145] op_sel_hi:[1,0]
	v_pk_mul_f32 v[18:19], v[18:19], v[144:145] op_sel_hi:[1,0]
	v_pk_mul_f32 v[16:17], v[16:17], v[144:145] op_sel_hi:[1,0]
	v_sub_f32_e32 v80, v80, v242
	v_sub_f32_e32 v81, v81, v242
	v_sub_f32_e32 v82, v82, v242
	v_sub_f32_e32 v83, v83, v242
	v_sub_f32_e32 v84, v84, v242
	v_sub_f32_e32 v85, v85, v242
	v_sub_f32_e32 v86, v86, v242
	v_sub_f32_e32 v87, v87, v242
	v_sub_f32_e32 v88, v88, v242
	v_sub_f32_e32 v89, v89, v242
	v_sub_f32_e32 v90, v90, v242
	v_sub_f32_e32 v91, v91, v242
	v_sub_f32_e32 v92, v92, v242
	v_sub_f32_e32 v93, v93, v242
	v_sub_f32_e32 v94, v94, v242
	v_sub_f32_e32 v95, v95, v242
	v_sub_f32_e32 v64, v64, v242
	v_sub_f32_e32 v65, v65, v242
	v_sub_f32_e32 v66, v66, v242
	v_sub_f32_e32 v67, v67, v242
	v_sub_f32_e32 v68, v68, v242
	v_sub_f32_e32 v69, v69, v242
	v_sub_f32_e32 v70, v70, v242
	v_sub_f32_e32 v71, v71, v242
	v_sub_f32_e32 v72, v72, v242
	v_sub_f32_e32 v73, v73, v242
	v_sub_f32_e32 v74, v74, v242
	v_sub_f32_e32 v75, v75, v242
	v_sub_f32_e32 v76, v76, v242
	v_sub_f32_e32 v77, v77, v242
	v_sub_f32_e32 v78, v78, v242
	v_sub_f32_e32 v79, v79, v242
	v_sub_f32_e32 v226, v226, v242
	v_sub_f32_e32 v227, v227, v242
	v_sub_f32_e32 v228, v228, v242
	v_sub_f32_e32 v229, v229, v242
	v_sub_f32_e32 v230, v230, v242
	v_sub_f32_e32 v231, v231, v242
	v_sub_f32_e32 v232, v232, v242
	v_sub_f32_e32 v233, v233, v242
	v_sub_f32_e32 v234, v234, v242
	v_sub_f32_e32 v235, v235, v242
	v_sub_f32_e32 v236, v236, v242
	v_sub_f32_e32 v237, v237, v242
	v_sub_f32_e32 v238, v238, v242
	v_sub_f32_e32 v239, v239, v242
	v_sub_f32_e32 v240, v240, v242
	v_sub_f32_e32 v241, v241, v242
	s_branch .LBB0_119
.Lrare_m1:
	v_max_f32_e32 v242, 0, v144
	v_exp_f32_e64 v152, -v242
	s_nop 0
	v_pk_mul_f32 v[14:15], v[14:15], v[152:153] op_sel_hi:[1,0]
	v_pk_mul_f32 v[12:13], v[12:13], v[152:153] op_sel_hi:[1,0]
	v_pk_mul_f32 v[10:11], v[10:11], v[152:153] op_sel_hi:[1,0]
	v_pk_mul_f32 v[8:9], v[8:9], v[152:153] op_sel_hi:[1,0]
	v_pk_mul_f32 v[6:7], v[6:7], v[152:153] op_sel_hi:[1,0]
	v_pk_mul_f32 v[4:5], v[4:5], v[152:153] op_sel_hi:[1,0]
	v_pk_mul_f32 v[2:3], v[2:3], v[152:153] op_sel_hi:[1,0]
	v_pk_mul_f32 v[0:1], v[0:1], v[152:153] op_sel_hi:[1,0]
	v_pk_mul_f32 v[62:63], v[62:63], v[152:153] op_sel_hi:[1,0]
	v_pk_mul_f32 v[60:61], v[60:61], v[152:153] op_sel_hi:[1,0]
	v_pk_mul_f32 v[58:59], v[58:59], v[152:153] op_sel_hi:[1,0]
	v_pk_mul_f32 v[56:57], v[56:57], v[152:153] op_sel_hi:[1,0]
	v_pk_mul_f32 v[54:55], v[54:55], v[152:153] op_sel_hi:[1,0]
	v_pk_mul_f32 v[52:53], v[52:53], v[152:153] op_sel_hi:[1,0]
	v_pk_mul_f32 v[50:51], v[50:51], v[152:153] op_sel_hi:[1,0]
	v_pk_mul_f32 v[48:49], v[48:49], v[152:153] op_sel_hi:[1,0]
	v_pk_mul_f32 v[46:47], v[46:47], v[152:153] op_sel_hi:[1,0]
	v_pk_mul_f32 v[44:45], v[44:45], v[152:153] op_sel_hi:[1,0]
	v_pk_mul_f32 v[42:43], v[42:43], v[152:153] op_sel_hi:[1,0]
	v_pk_mul_f32 v[40:41], v[40:41], v[152:153] op_sel_hi:[1,0]
	v_pk_mul_f32 v[38:39], v[38:39], v[152:153] op_sel_hi:[1,0]
	v_pk_mul_f32 v[36:37], v[36:37], v[152:153] op_sel_hi:[1,0]
	v_pk_mul_f32 v[34:35], v[34:35], v[152:153] op_sel_hi:[1,0]
	v_pk_mul_f32 v[32:33], v[32:33], v[152:153] op_sel_hi:[1,0]
	v_pk_mul_f32 v[30:31], v[30:31], v[152:153] op_sel_hi:[1,0]
	v_pk_mul_f32 v[28:29], v[28:29], v[152:153] op_sel_hi:[1,0]
	v_pk_mul_f32 v[26:27], v[26:27], v[152:153] op_sel_hi:[1,0]
	v_pk_mul_f32 v[24:25], v[24:25], v[152:153] op_sel_hi:[1,0]
	v_pk_mul_f32 v[22:23], v[22:23], v[152:153] op_sel_hi:[1,0]
	v_pk_mul_f32 v[20:21], v[20:21], v[152:153] op_sel_hi:[1,0]
	v_pk_mul_f32 v[18:19], v[18:19], v[152:153] op_sel_hi:[1,0]
	v_pk_mul_f32 v[16:17], v[16:17], v[152:153] op_sel_hi:[1,0]
	v_sub_f32_e32 v80, v80, v242
	v_sub_f32_e32 v81, v81, v242
	v_sub_f32_e32 v82, v82, v242
	v_sub_f32_e32 v83, v83, v242
	v_sub_f32_e32 v84, v84, v242
	v_sub_f32_e32 v85, v85, v242
	v_sub_f32_e32 v86, v86, v242
	v_sub_f32_e32 v87, v87, v242
	v_sub_f32_e32 v88, v88, v242
	v_sub_f32_e32 v89, v89, v242
	v_sub_f32_e32 v90, v90, v242
	v_sub_f32_e32 v91, v91, v242
	v_sub_f32_e32 v92, v92, v242
	v_sub_f32_e32 v93, v93, v242
	v_sub_f32_e32 v94, v94, v242
	v_sub_f32_e32 v95, v95, v242
	v_sub_f32_e32 v64, v64, v242
	v_sub_f32_e32 v65, v65, v242
	v_sub_f32_e32 v66, v66, v242
	v_sub_f32_e32 v67, v67, v242
	v_sub_f32_e32 v68, v68, v242
	v_sub_f32_e32 v69, v69, v242
	v_sub_f32_e32 v70, v70, v242
	v_sub_f32_e32 v71, v71, v242
	v_sub_f32_e32 v72, v72, v242
	v_sub_f32_e32 v73, v73, v242
	v_sub_f32_e32 v74, v74, v242
	v_sub_f32_e32 v75, v75, v242
	v_sub_f32_e32 v76, v76, v242
	v_sub_f32_e32 v77, v77, v242
	v_sub_f32_e32 v78, v78, v242
	v_sub_f32_e32 v79, v79, v242
	v_sub_f32_e32 v226, v226, v242
	v_sub_f32_e32 v227, v227, v242
	v_sub_f32_e32 v228, v228, v242
	v_sub_f32_e32 v229, v229, v242
	v_sub_f32_e32 v230, v230, v242
	v_sub_f32_e32 v231, v231, v242
	v_sub_f32_e32 v232, v232, v242
	v_sub_f32_e32 v233, v233, v242
	v_sub_f32_e32 v234, v234, v242
	v_sub_f32_e32 v235, v235, v242
	v_sub_f32_e32 v236, v236, v242
	v_sub_f32_e32 v237, v237, v242
	v_sub_f32_e32 v238, v238, v242
	v_sub_f32_e32 v239, v239, v242
	v_sub_f32_e32 v240, v240, v242
	v_sub_f32_e32 v241, v241, v242
	s_branch .LBB0_117

; __device__ __forceinline__ void finishSM(f32x16& p0, f32x16& p1, float alpha, float& l_reg, bf16x8& pa0, bf16x8& pa1, bf16x8& pa2, bf16x8& pa3) {
; #pragma unroll
;   for (int r = 0; r < 16; ++r) p1[r] = __builtin_amdgcn_exp2f(p1[r]);
;   float ps = 0;
; #pragma unroll
;   for (int r = 0; r < 16; ++r) ps += p0[r];
; #pragma unroll
;   for (int r = 0; r < 16; ++r) ps += p1[r];
;   { auto rr = __builtin_amdgcn_permlane32_swap(__float_as_uint(ps), __float_as_uint(ps), false, false);
;     ps = __uint_as_float(rr[0]) + __uint_as_float(rr[1]); }
;   l_reg = l_reg * alpha + ps;
;     ...
;   PK4(p0, 0, pa0); PK4(p0, 8, pa1); PK4(p1, 0, pa2); PK4(p1, 8, pa3);
;     ...
; }
; template <int BUFOFF>
; __device__ __forceinline__ void qkt_diff(f32x16& p0, f32x16& p1, const int* ka, const bf16x8* qr) {
;   typedef __attribute__((address_space(3))) const bf16x8* lp;
;   p0 = f32x16{}; p1 = f32x16{};
; #pragma unroll
;   for (int d0 = 0; d0 < 4; ++d0) {
;     const int a = ka[d0] + BUFOFF;
;     const bf16x8 b0 = *(lp)(a), b1 = *(lp)(a + 8192);
;     p0 = __builtin_amdgcn_mfma_f32_32x32x16_bf16(b0, qr[d0], p0, 0, 0, 0);
;     p1 = __builtin_amdgcn_mfma_f32_32x32x16_bf16(b1, qr[d0], p1, 0, 0, 0);
;   }
; }
.LBB0_129:
	s_mov_b32 s54, s47
	s_mov_b32 s47, s52
	ds_read_b128 v[64:67], v138 offset:16384
	ds_read_b128 v[68:71], v138 offset:24576
	ds_read_b128 v[170:173], v141 offset:16384
	ds_read_b128 v[188:191], v141 offset:24576
	s_waitcnt lgkmcnt(0)
	v_mfma_f32_32x32x16_bf16 v[80:95], v[64:67], v[108:111], v[226:241]
	v_add_f32_e32 v112, v144, v113
	v_mfma_f32_32x32x16_bf16 v[64:79], v[68:71], v[108:111], v[226:241]
	v_add_f32_e32 v243, v148, v155
	v_add_f32_e32 v244, v145, v152
	v_add_f32_e32 v245, v149, v156
	v_add_f32_e32 v246, v146, v153
	v_add_f32_e32 v247, v150, v158
	v_mfma_f32_32x32x16_bf16 v[80:95], v[170:173], v[104:107], v[80:95]
	v_add_f32_e32 v251, v147, v154
	v_add_f32_e32 v252, v151, v159
	v_mov_b32_e32 v132, v124
	v_add_f32_e32 v112, v128, v112
	v_mov_b32_e32 v162, v125
	v_mfma_f32_32x32x16_bf16 v[64:79], v[188:191], v[104:107], v[64:79]
	ds_read_b128 v[170:173], v140 offset:16384
	ds_read_b128 v[188:191], v140 offset:24576
	v_add_f32_e32 v243, v129, v243
	v_mov_b32_e32 v167, v120
	v_add_f32_e32 v244, v126, v244
	v_mov_b32_e32 v169, v121
	v_add_f32_e32 v245, v127, v245
	v_add_f32_e32 v246, v132, v246
	s_waitcnt lgkmcnt(0)
	v_mfma_f32_32x32x16_bf16 v[80:95], v[170:173], v[100:103], v[80:95]
	v_add_f32_e32 v247, v162, v247
	v_add_f32_e32 v251, v167, v251
	v_add_f32_e32 v252, v169, v252
	v_mfma_f32_32x32x16_bf16 v[64:79], v[188:191], v[100:103], v[64:79]
	ds_read_b128 v[170:173], v139 offset:16384
	ds_read_b128 v[188:191], v139 offset:24576
	s_waitcnt lgkmcnt(0)
	v_mfma_f32_32x32x16_bf16 v[80:95], v[170:173], v[96:99], v[80:95]
	v_mov_b32_e32 v170, v118
	v_mov_b32_e32 v171, v117
	v_mov_b32_e32 v172, v114
	v_mov_b32_e32 v173, v115
	v_add_f32_e32 v112, v170, v112
	v_add_f32_e32 v243, v119, v243
	v_add_f32_e32 v244, v116, v244
	v_mfma_f32_32x32x16_bf16 v[64:79], v[188:191], v[96:99], v[64:79]
	v_mov_b32_e32 v188, v122
	v_mov_b32_e32 v189, v123
	v_add_f32_e32 v245, v171, v245
	v_add_f32_e32 v246, v172, v246
	v_add_f32_e32 v247, v173, v247
	v_add_f32_e32 v251, v188, v251
	v_add_f32_e32 v252, v189, v252
	v_add_f32_e32 v112, v112, v243
	v_add_f32_e32 v244, v244, v245
	v_add_f32_e32 v246, v246, v247
	v_add_f32_e32 v251, v251, v252
	v_add_f32_e32 v112, v112, v244
	v_add_f32_e32 v246, v246, v251
	v_add_f32_e32 v117, v112, v246
	v_mov_b32_e32 v118, v117
	v_cvt_pk_bf16_f32 v112, v113, v155
	v_cvt_pk_bf16_f32 v113, v152, v156
	v_cvt_pk_bf16_f32 v114, v153, v158
	s_nop 1
	v_permlane32_swap_b32_e32 v117, v118
	v_cvt_pk_bf16_f32 v115, v154, v159
	v_cvt_pk_bf16_f32 v120, v144, v148
	v_cvt_pk_bf16_f32 v121, v145, v149
	v_cvt_pk_bf16_f32 v122, v146, v150
	v_cvt_pk_bf16_f32 v123, v147, v151
	v_cvt_pk_bf16_f32 v124, v128, v129
	v_cvt_pk_bf16_f32 v125, v126, v127
	v_cvt_pk_bf16_f32 v126, v132, v162
	v_cvt_pk_bf16_f32 v127, v167, v169
	v_cvt_pk_bf16_f32 v144, v170, v119
	v_cvt_pk_bf16_f32 v145, v116, v171
	v_cvt_pk_bf16_f32 v146, v172, v173
	v_cvt_pk_bf16_f32 v147, v188, v189
	s_add_u32 s4, s14, 0x2000000
	s_mov_b32 m0, s43
	s_addc_u32 s5, s15, 0
	s_mov_b64 s[56:57], s[14:15]
	s_lshl_b32 s52, s53, 14
	s_add_i32 s55, s42, s52
	s_nop 0
	global_load_lds_dwordx4 v134, s[56:57]
	s_mov_b32 m0, s44
	s_nop 0
	global_load_lds_dwordx4 v135, s[56:57]
	s_mov_b32 m0, s55
	s_nop 0
	global_load_lds_dwordx4 v136, s[4:5]
	s_add_i32 m0, s55, 0x2000
	s_nop 0
	global_load_lds_dwordx4 v137, s[4:5]
	s_lshl_b32 s55, s47, 14
	v_add_u32_e32 v132, s55, v133
	ds_read_b64_tr_b16 v[148:149], v132 offset:0
	ds_read_b64_tr_b16 v[150:151], v132 offset:0x800
	ds_read_b64_tr_b16 v[152:153], v132 offset:0x1000
	ds_read_b64_tr_b16 v[154:155], v132 offset:0x1800
	ds_read_b64_tr_b16 v[170:171], v132 offset:0x2000
	ds_read_b64_tr_b16 v[172:173], v132 offset:0x2800
	ds_read_b64_tr_b16 v[188:189], v132 offset:0x3000
	ds_read_b64_tr_b16 v[190:191], v132 offset:0x3800
	s_nop 0
	s_waitcnt lgkmcnt(6)
	v_mfma_f32_32x32x16_bf16 v[32:47], v[148:151], v[112:115], v[32:47]
	ds_read_b64_tr_b16 v[148:149], v132 offset:0x200
	ds_read_b64_tr_b16 v[150:151], v132 offset:0xa00
	s_waitcnt lgkmcnt(6)
	v_mfma_f32_32x32x16_bf16 v[32:47], v[152:155], v[120:123], v[32:47]
	ds_read_b64_tr_b16 v[152:153], v132 offset:0x1200
	ds_read_b64_tr_b16 v[154:155], v132 offset:0x1a00
	s_waitcnt lgkmcnt(6)
	v_mfma_f32_32x32x16_bf16 v[32:47], v[170:173], v[124:127], v[32:47]
	ds_read_b64_tr_b16 v[170:171], v132 offset:0x2200
	ds_read_b64_tr_b16 v[172:173], v132 offset:0x2a00
	s_waitcnt lgkmcnt(6)
	v_mfma_f32_32x32x16_bf16 v[32:47], v[188:191], v[144:147], v[32:47]
	ds_read_b64_tr_b16 v[188:189], v132 offset:0x3200
	ds_read_b64_tr_b16 v[190:191], v132 offset:0x3a00
	s_waitcnt lgkmcnt(6)
	v_mfma_f32_32x32x16_bf16 v[48:63], v[148:151], v[112:115], v[48:63]
	ds_read_b64_tr_b16 v[148:149], v132 offset:0x400
	ds_read_b64_tr_b16 v[150:151], v132 offset:0xc00
	s_waitcnt lgkmcnt(6)
	v_mfma_f32_32x32x16_bf16 v[48:63], v[152:155], v[120:123], v[48:63]
	ds_read_b64_tr_b16 v[152:153], v132 offset:0x1400
	ds_read_b64_tr_b16 v[154:155], v132 offset:0x1c00
	s_waitcnt lgkmcnt(6)
	v_mfma_f32_32x32x16_bf16 v[48:63], v[170:173], v[124:127], v[48:63]
	ds_read_b64_tr_b16 v[170:171], v132 offset:0x2400
	ds_read_b64_tr_b16 v[172:173], v132 offset:0x2c00
	s_waitcnt lgkmcnt(6)
	v_mfma_f32_32x32x16_bf16 v[48:63], v[188:191], v[144:147], v[48:63]
	ds_read_b64_tr_b16 v[188:189], v132 offset:0x3400
	ds_read_b64_tr_b16 v[190:191], v132 offset:0x3c00
	s_waitcnt lgkmcnt(6)
	v_mfma_f32_32x32x16_bf16 v[16:31], v[148:151], v[112:115], v[16:31]
	ds_read_b64_tr_b16 v[148:149], v132 offset:0x600
	ds_read_b64_tr_b16 v[150:151], v132 offset:0xe00
	s_waitcnt lgkmcnt(6)
	v_mfma_f32_32x32x16_bf16 v[16:31], v[152:155], v[120:123], v[16:31]
	ds_read_b64_tr_b16 v[152:153], v132 offset:0x1600
	ds_read_b64_tr_b16 v[154:155], v132 offset:0x1e00
	s_waitcnt lgkmcnt(6)
; template <int MLA>
; __device__ __forceinline__ void partialSM(f32x16& p0, f32x16& p1, float& m_reg, float& mn, float& alpha) {
;   constexpr float SCALE = AttC<MLA>::SCALE;
;   constexpr float C = SCALE * 1.4426950408889634f;
;   float pmax = p0[0];
; #pragma unroll
;   for (int r = 1; r < 16; ++r) pmax = fmaxf(pmax, p0[r]);
; #pragma unroll
;   for (int r = 0; r < 16; ++r) pmax = fmaxf(pmax, p1[r]);
;   { auto rr = __builtin_amdgcn_permlane32_swap(__float_as_uint(pmax), __float_as_uint(pmax), false, false);
;     pmax = fmaxf(__uint_as_float(rr[0]), __uint_as_float(rr[1])); }
;   if (__builtin_expect(__all(pmax - m_reg <= THR / SCALE), 1)) { mn = m_reg; alpha = 1.f; }
;   else { mn = fmaxf(m_reg, pmax); alpha = __builtin_amdgcn_exp2f((m_reg - mn) * C); m_reg = mn; }
;   float mnC = -mn * C;
; #pragma unroll
;   for (int r = 0; r < 16; ++r) p0[r] = fmaf(p0[r], C, mnC);
; #pragma unroll
;   for (int r = 0; r < 16; ++r) p1[r] = fmaf(p1[r], C, mnC);
; #pragma unroll
;   for (int r = 0; r < 16; ++r) p0[r] = __builtin_amdgcn_exp2f(p0[r]);
; }
; __device__ __forceinline__ void finishSM(f32x16& p0, f32x16& p1, float alpha, float& l_reg, bf16x8& pa0, bf16x8& pa1, bf16x8& pa2, bf16x8& pa3) {
; #pragma unroll
;   for (int r = 0; r < 16; ++r) p1[r] = __builtin_amdgcn_exp2f(p1[r]);
;   float ps = 0;
; #pragma unroll
;   for (int r = 0; r < 16; ++r) ps += p0[r];
; #pragma unroll
;   for (int r = 0; r < 16; ++r) ps += p1[r];
;   { auto rr = __builtin_amdgcn_permlane32_swap(__float_as_uint(ps), __float_as_uint(ps), false, false);
;     ps = __uint_as_float(rr[0]) + __uint_as_float(rr[1]); }
;   l_reg = l_reg * alpha + ps;
;     ...
;   PK4(p0, 0, pa0); PK4(p0, 8, pa1); PK4(p1, 0, pa2); PK4(p1, 8, pa3);
;     ...
; }
; template <int BUFOFF>
; __device__ __forceinline__ void qkt_diff(f32x16& p0, f32x16& p1, const int* ka, const bf16x8* qr) {
;   typedef __attribute__((address_space(3))) const bf16x8* lp;
;   p0 = f32x16{}; p1 = f32x16{};
; #pragma unroll
;   for (int d0 = 0; d0 < 4; ++d0) {
;     const int a = ka[d0] + BUFOFF;
;     const bf16x8 b0 = *(lp)(a), b1 = *(lp)(a + 8192);
;     p0 = __builtin_amdgcn_mfma_f32_32x32x16_bf16(b0, qr[d0], p0, 0, 0, 0);
;     p1 = __builtin_amdgcn_mfma_f32_32x32x16_bf16(b1, qr[d0], p1, 0, 0, 0);
;   }
; }
	v_mfma_f32_32x32x16_bf16 v[16:31], v[170:173], v[124:127], v[16:31]
	ds_read_b64_tr_b16 v[170:171], v132 offset:0x2600
	ds_read_b64_tr_b16 v[172:173], v132 offset:0x2e00
	s_waitcnt lgkmcnt(6)
	v_mfma_f32_32x32x16_bf16 v[16:31], v[188:191], v[144:147], v[16:31]
	ds_read_b64_tr_b16 v[188:189], v132 offset:0x3600
	ds_read_b64_tr_b16 v[190:191], v132 offset:0x3e00
	s_waitcnt lgkmcnt(6)
	v_mfma_f32_32x32x16_bf16 v[0:15], v[148:151], v[112:115], v[0:15]
	v_max_f32_e32 v112, v80, v81
	v_max3_f32 v112, v112, v82, v83
	v_max3_f32 v112, v112, v84, v85
	v_max3_f32 v112, v112, v86, v87
	v_max3_f32 v112, v112, v88, v89
	v_max3_f32 v112, v112, v90, v91
	v_max3_f32 v112, v112, v92, v93
	s_waitcnt lgkmcnt(4)
	v_mfma_f32_32x32x16_bf16 v[0:15], v[152:155], v[120:123], v[0:15]
	v_max3_f32 v112, v112, v94, v95
	v_max3_f32 v112, v112, v64, v65
	v_max3_f32 v112, v112, v66, v67
	v_max3_f32 v112, v112, v68, v69
	v_max3_f32 v112, v112, v70, v71
	v_max3_f32 v112, v112, v72, v73
	v_max3_f32 v112, v112, v74, v75
	v_max3_f32 v112, v112, v76, v77
	s_waitcnt lgkmcnt(2)
	v_mfma_f32_32x32x16_bf16 v[0:15], v[170:173], v[124:127], v[0:15]
	v_max3_f32 v112, v112, v78, v79
	v_mov_b32_e32 v113, v112
	s_nop 1
	v_permlane32_swap_b32_e32 v112, v113
	v_max_f32_e32 v112, v112, v113
	v_cmp_ge_f32_e32 vcc, s70, v112
	s_waitcnt lgkmcnt(0)
	v_mfma_f32_32x32x16_bf16 v[0:15], v[188:191], v[144:147], v[0:15]
	s_waitcnt vmcnt(0) lgkmcnt(0)
	s_barrier
	s_cmp_eq_u64 vcc, exec
	s_cbranch_scc0 .Lrare_d1
	v_mov_b32_e32 v116, 1.0
.LBB0_131:
	v_exp_f32_e32 v125, v64
	v_exp_f32_e32 v126, v65
	v_exp_f32_e32 v127, v66
	v_exp_f32_e32 v128, v67
	v_exp_f32_e32 v129, v68
	v_exp_f32_e32 v143, v69
	v_exp_f32_e32 v144, v70
	v_exp_f32_e32 v145, v71
	v_exp_f32_e32 v146, v72
	v_exp_f32_e32 v147, v73
	v_exp_f32_e32 v148, v74
	v_exp_f32_e32 v149, v75
	v_exp_f32_e32 v150, v76
	v_exp_f32_e32 v151, v80
	v_exp_f32_e32 v152, v81
	v_exp_f32_e32 v153, v82
	v_exp_f32_e32 v154, v83
	v_exp_f32_e32 v155, v84
	v_exp_f32_e32 v156, v85
	v_exp_f32_e32 v158, v86
	v_exp_f32_e32 v159, v87
	v_exp_f32_e32 v162, v88
	v_exp_f32_e32 v167, v89
	v_exp_f32_e32 v169, v90
	v_exp_f32_e32 v170, v91
	v_exp_f32_e32 v171, v92
	v_exp_f32_e32 v172, v93
	v_exp_f32_e32 v173, v94
	v_exp_f32_e32 v188, v95
	v_exp_f32_e32 v189, v77
	v_exp_f32_e32 v190, v78
	v_exp_f32_e32 v124, v79
	ds_read_b128 v[64:67], v138
	ds_read_b128 v[68:71], v138 offset:8192
	ds_read_b128 v[112:115], v141
	ds_read_b128 v[120:123], v141 offset:8192
	v_mov_b32_e32 v191, v125
	s_waitcnt lgkmcnt(0)
	v_mfma_f32_32x32x16_bf16 v[80:95], v[64:67], v[108:111], v[226:241]
	v_mfma_f32_32x32x16_bf16 v[64:79], v[68:71], v[108:111], v[226:241]
	v_mov_b32_e32 v192, v124
	v_mfma_f32_32x32x16_bf16 v[80:95], v[112:115], v[104:107], v[80:95]
	v_mfma_f32_32x32x16_bf16 v[64:79], v[120:123], v[104:107], v[64:79]
	ds_read_b128 v[112:115], v140
	ds_read_b128 v[120:123], v140 offset:8192
	s_waitcnt lgkmcnt(0)
	v_mfma_f32_32x32x16_bf16 v[80:95], v[112:115], v[100:103], v[80:95]
	v_mfma_f32_32x32x16_bf16 v[64:79], v[120:123], v[100:103], v[64:79]
	ds_read_b128 v[112:115], v139
	ds_read_b128 v[120:123], v139 offset:8192
	s_waitcnt lgkmcnt(0)
	v_mfma_f32_32x32x16_bf16 v[80:95], v[112:115], v[96:99], v[80:95]
	v_add_f32_e32 v112, v162, v151
	v_add_f32_e32 v243, v167, v152
	v_add_f32_e32 v244, v169, v153
	v_add_f32_e32 v245, v170, v154
	v_add_f32_e32 v246, v171, v155
	v_add_f32_e32 v247, v172, v156
	v_add_f32_e32 v251, v173, v158
	v_add_f32_e32 v252, v188, v159
	v_add_f32_e32 v112, v191, v112
	v_add_f32_e32 v243, v126, v243
	v_add_f32_e32 v244, v127, v244
	v_add_f32_e32 v245, v128, v245
	v_add_f32_e32 v246, v129, v246
	v_add_f32_e32 v247, v143, v247
	v_add_f32_e32 v251, v144, v251
	v_add_f32_e32 v252, v145, v252
	v_add_f32_e32 v112, v146, v112
	v_add_f32_e32 v243, v147, v243
	v_mfma_f32_32x32x16_bf16 v[64:79], v[120:123], v[96:99], v[64:79]
	v_add_f32_e32 v244, v148, v244
	v_add_f32_e32 v245, v149, v245
	v_add_f32_e32 v246, v150, v246
	v_add_f32_e32 v247, v189, v247
	v_add_f32_e32 v251, v190, v251
	v_add_f32_e32 v252, v192, v252
	v_add_f32_e32 v112, v112, v243
	v_add_f32_e32 v244, v244, v245
	v_add_f32_e32 v246, v246, v247
	v_add_f32_e32 v251, v251, v252
	v_add_f32_e32 v112, v112, v244
	v_add_f32_e32 v246, v246, v251
	v_add_f32_e32 v120, v112, v246
	v_mov_b32_e32 v121, v120
	v_cvt_pk_bf16_f32 v112, v151, v152
	v_cvt_pk_bf16_f32 v113, v153, v154
	v_cvt_pk_bf16_f32 v114, v155, v156
	v_cvt_pk_bf16_f32 v115, v158, v159
	s_nop 1
	v_permlane32_swap_b32_e32 v120, v121
	v_cvt_pk_bf16_f32 v122, v162, v167
	v_cvt_pk_bf16_f32 v123, v169, v170
	v_cvt_pk_bf16_f32 v124, v171, v172
	v_cvt_pk_bf16_f32 v125, v173, v188
	v_cvt_pk_bf16_f32 v126, v191, v126
	v_cvt_pk_bf16_f32 v127, v127, v128
	v_cvt_pk_bf16_f32 v128, v129, v143
	v_cvt_pk_bf16_f32 v129, v144, v145
	v_cvt_pk_bf16_f32 v144, v146, v147
	v_cvt_pk_bf16_f32 v145, v148, v149
	v_cvt_pk_bf16_f32 v146, v150, v189
	v_cvt_pk_bf16_f32 v147, v190, v192
	s_nop 0
	s_add_u32 s4, s14, 0x20000
	s_addc_u32 s5, s15, 0
	s_add_u32 s56, s14, 0x2020000
	s_mov_b32 m0, s16
	s_addc_u32 s57, s15, 0
	s_add_i32 s55, s42, s55
	s_nop 0
	global_load_lds_dwordx4 v134, s[4:5]
	s_mov_b32 m0, s17
	s_nop 0
	global_load_lds_dwordx4 v135, s[4:5]
	s_mov_b32 m0, s55
	s_nop 0
	global_load_lds_dwordx4 v136, s[56:57]
	s_add_i32 m0, s55, 0x2000
	s_nop 0
	global_load_lds_dwordx4 v137, s[56:57]
	v_lshl_add_u32 v143, s54, 14, v133
	ds_read_b64_tr_b16 v[148:149], v143 offset:0
	ds_read_b64_tr_b16 v[150:151], v143 offset:0x800
	ds_read_b64_tr_b16 v[152:153], v143 offset:0x1000
	ds_read_b64_tr_b16 v[154:155], v143 offset:0x1800
	ds_read_b64_tr_b16 v[170:171], v143 offset:0x2000
	ds_read_b64_tr_b16 v[172:173], v143 offset:0x2800
	ds_read_b64_tr_b16 v[188:189], v143 offset:0x3000
	ds_read_b64_tr_b16 v[190:191], v143 offset:0x3800
	s_nop 0
	s_waitcnt lgkmcnt(6)
; #define SBAR() __builtin_amdgcn_sched_barrier(0)
; template <int MLA>
; __device__ __forceinline__ void partialSM(f32x16& p0, f32x16& p1, float& m_reg, float& mn, float& alpha) {
;     ...
;   float pmax = p0[0];
; #pragma unroll
;   for (int r = 1; r < 16; ++r) pmax = fmaxf(pmax, p0[r]);
; #pragma unroll
;   for (int r = 0; r < 16; ++r) pmax = fmaxf(pmax, p1[r]);
;   { auto rr = __builtin_amdgcn_permlane32_swap(__float_as_uint(pmax), __float_as_uint(pmax), false, false);
;     pmax = fmaxf(__uint_as_float(rr[0]), __uint_as_float(rr[1])); }
;   if (__builtin_expect(__all(pmax - m_reg <= THR / SCALE), 1)) { mn = m_reg; alpha = 1.f; }
;   else { mn = fmaxf(m_reg, pmax); alpha = __builtin_amdgcn_exp2f((m_reg - mn) * C); m_reg = mn; }
; template <int D0> __device__ __forceinline__ void pv_one_t(f32x16& od, int vb, bf16x8 pa0, bf16x8 pa1, bf16x8 pa2, bf16x8 pa3) {
;   const s16x4 l0 = tr_read<v_rd_off(D0, 0, 0)>(vb), h0 = tr_read<v_rd_off(D0, 0, 1)>(vb), l1 = tr_read<v_rd_off(D0, 1, 0)>(vb), h1 = tr_read<v_rd_off(D0, 1, 1)>(vb);
;   const s16x4 l2 = tr_read<v_rd_off(D0, 2, 0)>(vb), h2 = tr_read<v_rd_off(D0, 2, 1)>(vb), l3 = tr_read<v_rd_off(D0, 3, 0)>(vb), h3 = tr_read<v_rd_off(D0, 3, 1)>(vb);
;   asm volatile("s_waitcnt lgkmcnt(0)" ::: "memory"); SBAR();
;     ...
;   od = __builtin_amdgcn_mfma_f32_32x32x16_bf16(PK(l0, h0), pa0, od, 0, 0, 0);
;   od = __builtin_amdgcn_mfma_f32_32x32x16_bf16(PK(l1, h1), pa1, od, 0, 0, 0);
;   od = __builtin_amdgcn_mfma_f32_32x32x16_bf16(PK(l2, h2), pa2, od, 0, 0, 0);
;   od = __builtin_amdgcn_mfma_f32_32x32x16_bf16(PK(l3, h3), pa3, od, 0, 0, 0);
;     ...
; }
	v_mfma_f32_32x32x16_bf16 v[32:47], v[148:151], v[112:115], v[32:47]
	ds_read_b64_tr_b16 v[148:149], v143 offset:0x200
	ds_read_b64_tr_b16 v[150:151], v143 offset:0xa00
	s_waitcnt lgkmcnt(6)
	v_mfma_f32_32x32x16_bf16 v[32:47], v[152:155], v[122:125], v[32:47]
	ds_read_b64_tr_b16 v[152:153], v143 offset:0x1200
	ds_read_b64_tr_b16 v[154:155], v143 offset:0x1a00
	s_waitcnt lgkmcnt(6)
	v_mfma_f32_32x32x16_bf16 v[32:47], v[170:173], v[126:129], v[32:47]
	ds_read_b64_tr_b16 v[170:171], v143 offset:0x2200
	ds_read_b64_tr_b16 v[172:173], v143 offset:0x2a00
	s_waitcnt lgkmcnt(6)
	v_mfma_f32_32x32x16_bf16 v[32:47], v[188:191], v[144:147], v[32:47]
	ds_read_b64_tr_b16 v[188:189], v143 offset:0x3200
	ds_read_b64_tr_b16 v[190:191], v143 offset:0x3a00
	s_waitcnt lgkmcnt(6)
	v_mfma_f32_32x32x16_bf16 v[48:63], v[148:151], v[112:115], v[48:63]
	ds_read_b64_tr_b16 v[148:149], v143 offset:0x400
	ds_read_b64_tr_b16 v[150:151], v143 offset:0xc00
	s_waitcnt lgkmcnt(6)
	v_mfma_f32_32x32x16_bf16 v[48:63], v[152:155], v[122:125], v[48:63]
	ds_read_b64_tr_b16 v[152:153], v143 offset:0x1400
	ds_read_b64_tr_b16 v[154:155], v143 offset:0x1c00
	s_waitcnt lgkmcnt(6)
	v_mfma_f32_32x32x16_bf16 v[48:63], v[170:173], v[126:129], v[48:63]
	ds_read_b64_tr_b16 v[170:171], v143 offset:0x2400
	ds_read_b64_tr_b16 v[172:173], v143 offset:0x2c00
	s_waitcnt lgkmcnt(6)
	v_mfma_f32_32x32x16_bf16 v[48:63], v[188:191], v[144:147], v[48:63]
	ds_read_b64_tr_b16 v[188:189], v143 offset:0x3400
	ds_read_b64_tr_b16 v[190:191], v143 offset:0x3c00
	s_waitcnt lgkmcnt(6)
	v_mfma_f32_32x32x16_bf16 v[16:31], v[148:151], v[112:115], v[16:31]
	ds_read_b64_tr_b16 v[148:149], v143 offset:0x600
	ds_read_b64_tr_b16 v[150:151], v143 offset:0xe00
	s_waitcnt lgkmcnt(6)
	v_mfma_f32_32x32x16_bf16 v[16:31], v[152:155], v[122:125], v[16:31]
	ds_read_b64_tr_b16 v[152:153], v143 offset:0x1600
	ds_read_b64_tr_b16 v[154:155], v143 offset:0x1e00
	s_waitcnt lgkmcnt(6)
	v_mfma_f32_32x32x16_bf16 v[16:31], v[170:173], v[126:129], v[16:31]
	ds_read_b64_tr_b16 v[170:171], v143 offset:0x2600
	ds_read_b64_tr_b16 v[172:173], v143 offset:0x2e00
	s_waitcnt lgkmcnt(6)
	v_mfma_f32_32x32x16_bf16 v[16:31], v[188:191], v[144:147], v[16:31]
	ds_read_b64_tr_b16 v[188:189], v143 offset:0x3600
	ds_read_b64_tr_b16 v[190:191], v143 offset:0x3e00
	s_waitcnt lgkmcnt(6)
	v_mfma_f32_32x32x16_bf16 v[0:15], v[148:151], v[112:115], v[0:15]
	v_max_f32_e32 v112, v80, v81
	v_max3_f32 v112, v112, v82, v83
	v_max3_f32 v112, v112, v84, v85
	v_max3_f32 v112, v112, v86, v87
	v_max3_f32 v112, v112, v88, v89
	v_max3_f32 v112, v112, v90, v91
	v_max3_f32 v112, v112, v92, v93
	s_waitcnt lgkmcnt(4)
	v_mfma_f32_32x32x16_bf16 v[0:15], v[152:155], v[122:125], v[0:15]
	v_max3_f32 v112, v112, v94, v95
	v_max3_f32 v112, v112, v64, v65
	v_max3_f32 v112, v112, v66, v67
	v_max3_f32 v112, v112, v68, v69
	v_max3_f32 v112, v112, v70, v71
	v_max3_f32 v112, v112, v72, v73
	v_max3_f32 v112, v112, v74, v75
	v_max3_f32 v112, v112, v76, v77
	s_waitcnt lgkmcnt(2)
	v_mfma_f32_32x32x16_bf16 v[0:15], v[170:173], v[126:129], v[0:15]
	v_max3_f32 v112, v112, v78, v79
	v_mov_b32_e32 v113, v112
	s_nop 1
	v_permlane32_swap_b32_e32 v112, v113
	v_max_f32_e32 v112, v112, v113
	v_cmp_ge_f32_e32 vcc, s70, v112
	s_waitcnt lgkmcnt(0)
	v_mfma_f32_32x32x16_bf16 v[0:15], v[188:191], v[144:147], v[0:15]
	s_waitcnt vmcnt(0) lgkmcnt(0)
	s_barrier
	s_cmp_eq_u64 vcc, exec
	s_cbranch_scc0 .Lrare_d2
	v_mov_b32_e32 v112, 1.0

; template <int MLA>
; __device__ __forceinline__ void partialSM(f32x16& p0, f32x16& p1, float& m_reg, float& mn, float& alpha) {
;     ...
;   if (__builtin_expect(__all(pmax - m_reg <= THR / SCALE), 1)) { mn = m_reg; alpha = 1.f; }
;   else { mn = fmaxf(m_reg, pmax); alpha = __builtin_amdgcn_exp2f((m_reg - mn) * C); m_reg = mn; }
;   float mnC = -mn * C;
; #pragma unroll
;   for (int r = 0; r < 16; ++r) p0[r] = fmaf(p0[r], C, mnC);
; #pragma unroll
;   for (int r = 0; r < 16; ++r) p1[r] = fmaf(p1[r], C, mnC);
.Lrare_d2:
	v_max_f32_e32 v242, 0, v112
	v_exp_f32_e64 v112, -v242
	s_nop 0
	v_pk_mul_f32 v[46:47], v[46:47], v[112:113] op_sel_hi:[1,0]
	v_pk_mul_f32 v[44:45], v[44:45], v[112:113] op_sel_hi:[1,0]
	v_pk_mul_f32 v[42:43], v[42:43], v[112:113] op_sel_hi:[1,0]
	v_pk_mul_f32 v[40:41], v[40:41], v[112:113] op_sel_hi:[1,0]
	v_pk_mul_f32 v[38:39], v[38:39], v[112:113] op_sel_hi:[1,0]
	v_pk_mul_f32 v[36:37], v[36:37], v[112:113] op_sel_hi:[1,0]
	v_pk_mul_f32 v[34:35], v[34:35], v[112:113] op_sel_hi:[1,0]
	v_pk_mul_f32 v[32:33], v[32:33], v[112:113] op_sel_hi:[1,0]
	v_pk_mul_f32 v[62:63], v[62:63], v[112:113] op_sel_hi:[1,0]
	v_pk_mul_f32 v[60:61], v[60:61], v[112:113] op_sel_hi:[1,0]
	v_pk_mul_f32 v[58:59], v[58:59], v[112:113] op_sel_hi:[1,0]
	v_pk_mul_f32 v[56:57], v[56:57], v[112:113] op_sel_hi:[1,0]
	v_pk_mul_f32 v[54:55], v[54:55], v[112:113] op_sel_hi:[1,0]
	v_pk_mul_f32 v[52:53], v[52:53], v[112:113] op_sel_hi:[1,0]
	v_pk_mul_f32 v[50:51], v[50:51], v[112:113] op_sel_hi:[1,0]
	v_pk_mul_f32 v[48:49], v[48:49], v[112:113] op_sel_hi:[1,0]
	v_pk_mul_f32 v[30:31], v[30:31], v[112:113] op_sel_hi:[1,0]
	v_pk_mul_f32 v[28:29], v[28:29], v[112:113] op_sel_hi:[1,0]
	v_pk_mul_f32 v[26:27], v[26:27], v[112:113] op_sel_hi:[1,0]
	v_pk_mul_f32 v[24:25], v[24:25], v[112:113] op_sel_hi:[1,0]
	v_pk_mul_f32 v[22:23], v[22:23], v[112:113] op_sel_hi:[1,0]
	v_pk_mul_f32 v[20:21], v[20:21], v[112:113] op_sel_hi:[1,0]
	v_pk_mul_f32 v[18:19], v[18:19], v[112:113] op_sel_hi:[1,0]
	v_pk_mul_f32 v[16:17], v[16:17], v[112:113] op_sel_hi:[1,0]
	v_pk_mul_f32 v[14:15], v[14:15], v[112:113] op_sel_hi:[1,0]
	v_pk_mul_f32 v[12:13], v[12:13], v[112:113] op_sel_hi:[1,0]
	v_pk_mul_f32 v[10:11], v[10:11], v[112:113] op_sel_hi:[1,0]
	v_pk_mul_f32 v[8:9], v[8:9], v[112:113] op_sel_hi:[1,0]
	v_pk_mul_f32 v[6:7], v[6:7], v[112:113] op_sel_hi:[1,0]
	v_pk_mul_f32 v[4:5], v[4:5], v[112:113] op_sel_hi:[1,0]
	v_pk_mul_f32 v[2:3], v[2:3], v[112:113] op_sel_hi:[1,0]
	v_pk_mul_f32 v[0:1], v[0:1], v[112:113] op_sel_hi:[1,0]
	v_sub_f32_e32 v80, v80, v242
	v_sub_f32_e32 v81, v81, v242
	v_sub_f32_e32 v82, v82, v242
	v_sub_f32_e32 v83, v83, v242
	v_sub_f32_e32 v84, v84, v242
	v_sub_f32_e32 v85, v85, v242
	v_sub_f32_e32 v86, v86, v242
	v_sub_f32_e32 v87, v87, v242
	v_sub_f32_e32 v88, v88, v242
	v_sub_f32_e32 v89, v89, v242
	v_sub_f32_e32 v90, v90, v242
	v_sub_f32_e32 v91, v91, v242
	v_sub_f32_e32 v92, v92, v242
	v_sub_f32_e32 v93, v93, v242
	v_sub_f32_e32 v94, v94, v242
	v_sub_f32_e32 v95, v95, v242
	v_sub_f32_e32 v64, v64, v242
	v_sub_f32_e32 v65, v65, v242
	v_sub_f32_e32 v66, v66, v242
	v_sub_f32_e32 v67, v67, v242
	v_sub_f32_e32 v68, v68, v242
	v_sub_f32_e32 v69, v69, v242
	v_sub_f32_e32 v70, v70, v242
	v_sub_f32_e32 v71, v71, v242
	v_sub_f32_e32 v72, v72, v242
	v_sub_f32_e32 v73, v73, v242
	v_sub_f32_e32 v74, v74, v242
	v_sub_f32_e32 v75, v75, v242
	v_sub_f32_e32 v76, v76, v242
	v_sub_f32_e32 v77, v77, v242
	v_sub_f32_e32 v78, v78, v242
	v_sub_f32_e32 v79, v79, v242
	v_sub_f32_e32 v226, v226, v242
	v_sub_f32_e32 v227, v227, v242
	v_sub_f32_e32 v228, v228, v242
	v_sub_f32_e32 v229, v229, v242
	v_sub_f32_e32 v230, v230, v242
	v_sub_f32_e32 v231, v231, v242
	v_sub_f32_e32 v232, v232, v242
	v_sub_f32_e32 v233, v233, v242
	v_sub_f32_e32 v234, v234, v242
	v_sub_f32_e32 v235, v235, v242
	v_sub_f32_e32 v236, v236, v242
	v_sub_f32_e32 v237, v237, v242
	v_sub_f32_e32 v238, v238, v242
	v_sub_f32_e32 v239, v239, v242
	v_sub_f32_e32 v240, v240, v242
	v_sub_f32_e32 v241, v241, v242
	s_branch .LBB0_133
.Lrare_d1:
	v_max_f32_e32 v242, 0, v112
	v_exp_f32_e64 v116, -v242
	s_nop 0
	v_pk_mul_f32 v[46:47], v[46:47], v[116:117] op_sel_hi:[1,0]
	v_pk_mul_f32 v[44:45], v[44:45], v[116:117] op_sel_hi:[1,0]
	v_pk_mul_f32 v[42:43], v[42:43], v[116:117] op_sel_hi:[1,0]
	v_pk_mul_f32 v[40:41], v[40:41], v[116:117] op_sel_hi:[1,0]
	v_pk_mul_f32 v[38:39], v[38:39], v[116:117] op_sel_hi:[1,0]
	v_pk_mul_f32 v[36:37], v[36:37], v[116:117] op_sel_hi:[1,0]
	v_pk_mul_f32 v[34:35], v[34:35], v[116:117] op_sel_hi:[1,0]
	v_pk_mul_f32 v[32:33], v[32:33], v[116:117] op_sel_hi:[1,0]
	v_pk_mul_f32 v[62:63], v[62:63], v[116:117] op_sel_hi:[1,0]
	v_pk_mul_f32 v[60:61], v[60:61], v[116:117] op_sel_hi:[1,0]
	v_pk_mul_f32 v[58:59], v[58:59], v[116:117] op_sel_hi:[1,0]
	v_pk_mul_f32 v[56:57], v[56:57], v[116:117] op_sel_hi:[1,0]
	v_pk_mul_f32 v[54:55], v[54:55], v[116:117] op_sel_hi:[1,0]
	v_pk_mul_f32 v[52:53], v[52:53], v[116:117] op_sel_hi:[1,0]
	v_pk_mul_f32 v[50:51], v[50:51], v[116:117] op_sel_hi:[1,0]
	v_pk_mul_f32 v[48:49], v[48:49], v[116:117] op_sel_hi:[1,0]
	v_pk_mul_f32 v[30:31], v[30:31], v[116:117] op_sel_hi:[1,0]
	v_pk_mul_f32 v[28:29], v[28:29], v[116:117] op_sel_hi:[1,0]
	v_pk_mul_f32 v[26:27], v[26:27], v[116:117] op_sel_hi:[1,0]
	v_pk_mul_f32 v[24:25], v[24:25], v[116:117] op_sel_hi:[1,0]
	v_pk_mul_f32 v[22:23], v[22:23], v[116:117] op_sel_hi:[1,0]
	v_pk_mul_f32 v[20:21], v[20:21], v[116:117] op_sel_hi:[1,0]
	v_pk_mul_f32 v[18:19], v[18:19], v[116:117] op_sel_hi:[1,0]
	v_pk_mul_f32 v[16:17], v[16:17], v[116:117] op_sel_hi:[1,0]
	v_pk_mul_f32 v[14:15], v[14:15], v[116:117] op_sel_hi:[1,0]
	v_pk_mul_f32 v[12:13], v[12:13], v[116:117] op_sel_hi:[1,0]
	v_pk_mul_f32 v[10:11], v[10:11], v[116:117] op_sel_hi:[1,0]
	v_pk_mul_f32 v[8:9], v[8:9], v[116:117] op_sel_hi:[1,0]
	v_pk_mul_f32 v[6:7], v[6:7], v[116:117] op_sel_hi:[1,0]
	v_pk_mul_f32 v[4:5], v[4:5], v[116:117] op_sel_hi:[1,0]
	v_pk_mul_f32 v[2:3], v[2:3], v[116:117] op_sel_hi:[1,0]
	v_pk_mul_f32 v[0:1], v[0:1], v[116:117] op_sel_hi:[1,0]
	v_sub_f32_e32 v80, v80, v242
	v_sub_f32_e32 v81, v81, v242
	v_sub_f32_e32 v82, v82, v242
	v_sub_f32_e32 v83, v83, v242
	v_sub_f32_e32 v84, v84, v242
	v_sub_f32_e32 v85, v85, v242
	v_sub_f32_e32 v86, v86, v242
	v_sub_f32_e32 v87, v87, v242
	v_sub_f32_e32 v88, v88, v242
	v_sub_f32_e32 v89, v89, v242
	v_sub_f32_e32 v90, v90, v242
	v_sub_f32_e32 v91, v91, v242
	v_sub_f32_e32 v92, v92, v242
	v_sub_f32_e32 v93, v93, v242
	v_sub_f32_e32 v94, v94, v242
	v_sub_f32_e32 v95, v95, v242
	v_sub_f32_e32 v64, v64, v242
	v_sub_f32_e32 v65, v65, v242
	v_sub_f32_e32 v66, v66, v242
	v_sub_f32_e32 v67, v67, v242
	v_sub_f32_e32 v68, v68, v242
	v_sub_f32_e32 v69, v69, v242
	v_sub_f32_e32 v70, v70, v242
	v_sub_f32_e32 v71, v71, v242
	v_sub_f32_e32 v72, v72, v242
	v_sub_f32_e32 v73, v73, v242
	v_sub_f32_e32 v74, v74, v242
	v_sub_f32_e32 v75, v75, v242
	v_sub_f32_e32 v76, v76, v242
	v_sub_f32_e32 v77, v77, v242
	v_sub_f32_e32 v78, v78, v242
	v_sub_f32_e32 v79, v79, v242
	v_sub_f32_e32 v226, v226, v242
	v_sub_f32_e32 v227, v227, v242
	v_sub_f32_e32 v228, v228, v242
	v_sub_f32_e32 v229, v229, v242
	v_sub_f32_e32 v230, v230, v242
	v_sub_f32_e32 v231, v231, v242
	v_sub_f32_e32 v232, v232, v242
	v_sub_f32_e32 v233, v233, v242
	v_sub_f32_e32 v234, v234, v242
	v_sub_f32_e32 v235, v235, v242
	v_sub_f32_e32 v236, v236, v242
	v_sub_f32_e32 v237, v237, v242
	v_sub_f32_e32 v238, v238, v242
	v_sub_f32_e32 v239, v239, v242
	v_sub_f32_e32 v240, v240, v242
	v_sub_f32_e32 v241, v241, v242
	s_branch .LBB0_131
